# grid barrier: all waiters poll the monotone TOP arrival counter against (gen+1)*nx; TOPGEN and XGEN adds removed (v43 base, no lora loader change)
# speedup vs baseline: 1.0035x; 1.0035x over previous
.LBB0_85:
	s_or_b64 exec, exec, s[8:9]
	s_waitcnt vmcnt(0)
	v_readfirstlane_b32 s3, v3
	v_sub_u32_e32 v4, 0, v2
	s_nop 0
	v_add_u32_e32 v3, s3, v1
	v_cvt_f32_u32_e32 v1, v2
	v_rcp_iflag_f32_e32 v1, v1
	s_nop 0
	v_mul_f32_e32 v1, 0x4f7ffffe, v1
	v_cvt_u32_f32_e32 v1, v1
	v_mul_lo_u32 v4, v4, v1
	v_mul_hi_u32 v4, v1, v4
	v_add_u32_e32 v1, v1, v4
	v_mul_hi_u32 v1, v3, v1
	v_mul_lo_u32 v4, v1, v2
	v_sub_u32_e32 v4, v3, v4
	v_cmp_ge_u32_e32 vcc, v4, v2
	v_add_u32_e32 v5, 1, v1
	s_nop 0
	v_cndmask_b32_e32 v1, v1, v5, vcc
	v_sub_u32_e32 v5, v4, v2
	v_cndmask_b32_e32 v4, v4, v5, vcc
	v_cmp_ge_u32_e32 vcc, v4, v2
	v_add_u32_e32 v4, 1, v1
	s_nop 0
	v_cndmask_b32_e32 v1, v1, v4, vcc
	v_add_u32_e32 v4, 1, v3
	v_mad_u64_u32 v[2:3], s[6:7], v2, v1, v[2:3]
	v_cmp_ne_u32_e32 vcc, v4, v2
	s_and_saveexec_b64 s[6:7], vcc
	s_xor_b64 s[6:7], exec, s[6:7]
	s_cbranch_execz .LBB0_99
	v_mad_u32_u24 v4, v1, v0, v0
	v_mov_b32_e32 v0, 0x3000
	global_load_dword v0, v0, s[92:93] offset:1024 sc1
	s_add_u32 s12, s92, 0x3400
	s_addc_u32 s13, s93, 0
	s_waitcnt vmcnt(0)
	v_cmp_lt_u32_e32 vcc, v0, v4
	s_and_saveexec_b64 s[8:9], vcc
	s_cbranch_execz .LBB0_98
	s_mov_b32 s3, 1
	s_mov_b64 s[56:57], 0
	v_mov_b32_e32 v0, 0
	s_branch .LBB0_89

.LBB0_93:
	global_load_dword v2, v0, s[12:13] sc1
	s_add_i32 s3, s3, 1
	s_mov_b64 s[80:81], -1
	s_waitcnt vmcnt(0)
	v_cmp_ge_u32_e32 vcc, v2, v4
	s_orn2_b64 s[62:63], vcc, exec
	s_branch .LBB0_88

.LBB0_102:
	s_or_b64 exec, exec, s[8:9]
	s_waitcnt vmcnt(0)
	v_readfirstlane_b32 s3, v2
	v_cvt_f32_u32_e32 v2, v0
	v_sub_u32_e32 v3, 0, v0
	v_add_u32_e32 v1, s3, v1
	s_add_u32 s8, s92, 0x3400
	v_rcp_iflag_f32_e32 v2, v2
	s_addc_u32 s9, s93, 0
	s_mov_b64 s[12:13], 0
	v_mul_f32_e32 v2, 0x4f7ffffe, v2
	v_cvt_u32_f32_e32 v2, v2
	v_mul_lo_u32 v3, v3, v2
	v_mul_hi_u32 v3, v2, v3
	v_add_u32_e32 v2, v2, v3
	v_mul_hi_u32 v2, v1, v2
	v_mul_lo_u32 v3, v2, v0
	v_sub_u32_e32 v3, v1, v3
	v_cmp_ge_u32_e32 vcc, v3, v0
	v_add_u32_e32 v4, 1, v2
	s_nop 0
	v_cndmask_b32_e32 v2, v2, v4, vcc
	v_sub_u32_e32 v4, v3, v0
	v_cndmask_b32_e32 v3, v3, v4, vcc
	v_cmp_ge_u32_e32 vcc, v3, v0
	v_add_u32_e32 v3, 1, v2
	s_nop 0
	v_cndmask_b32_e32 v2, v2, v3, vcc
	v_add_u32_e32 v3, 1, v1
	v_mad_u64_u32 v[0:1], s[6:7], v0, v2, v[0:1]
	v_cmp_ne_u32_e32 vcc, v3, v0
	v_mov_b32_e32 v3, v0
	v_mov_b64_e32 v[0:1], s[8:9]
	s_and_saveexec_b64 s[6:7], vcc
	s_cbranch_execz .LBB0_114
	v_mov_b32_e32 v0, 0
	global_load_dword v1, v0, s[8:9] sc1
	s_mov_b64 s[60:61], 0
	s_waitcnt vmcnt(0)
	v_cmp_lt_u32_e32 vcc, v1, v3
	s_and_saveexec_b64 s[56:57], vcc
	s_cbranch_execz .LBB0_113
	s_add_u32 s12, s92, 0x200
	s_addc_u32 s13, s93, 0
	s_mov_b32 s3, 1
	s_branch .LBB0_106

.LBB0_110:
	global_load_dword v1, v0, s[8:9] sc1
	s_add_i32 s3, s3, 1
	s_mov_b64 s[80:81], -1
	s_waitcnt vmcnt(0)
	v_cmp_ge_u32_e32 vcc, v1, v3
	s_orn2_b64 s[94:95], vcc, exec
	s_branch .LBB0_105

.LBB0_116:
	s_or_b64 exec, exec, s[6:7]
	s_mov_b64 s[6:7], exec
	v_mbcnt_lo_u32_b32 v0, s6, 0
	v_mbcnt_hi_u32_b32 v0, s7, v0
	v_cmp_eq_u32_e32 vcc, 0, v0
	s_waitcnt vmcnt(0)
	buffer_inv sc1
	s_and_saveexec_b64 s[8:9], vcc
	s_cbranch_execz .LBB0_118
	s_bcnt1_i32_b64 s3, s[6:7]
	v_mov_b32_e32 v0, 0x2000
	v_mov_b32_e32 v1, s3
.LBB0_118:
	s_or_b64 exec, exec, s[8:9]
	s_waitcnt vmcnt(0)

.LBB0_140:
	s_or_b64 exec, exec, s[12:13]
	s_waitcnt vmcnt(0)
	v_readfirstlane_b32 s0, v3
	v_sub_u32_e32 v4, 0, v2
	s_nop 0
	v_add_u32_e32 v3, s0, v1
	v_cvt_f32_u32_e32 v1, v2
	v_rcp_iflag_f32_e32 v1, v1
	s_nop 0
	v_mul_f32_e32 v1, 0x4f7ffffe, v1
	v_cvt_u32_f32_e32 v1, v1
	v_mul_lo_u32 v4, v4, v1
	v_mul_hi_u32 v4, v1, v4
	v_add_u32_e32 v1, v1, v4
	v_mul_hi_u32 v1, v3, v1
	v_mul_lo_u32 v4, v1, v2
	v_sub_u32_e32 v4, v3, v4
	v_cmp_ge_u32_e32 vcc, v4, v2
	v_add_u32_e32 v5, 1, v1
	s_nop 0
	v_cndmask_b32_e32 v1, v1, v5, vcc
	v_sub_u32_e32 v5, v4, v2
	v_cndmask_b32_e32 v4, v4, v5, vcc
	v_cmp_ge_u32_e32 vcc, v4, v2
	v_add_u32_e32 v4, 1, v1
	s_nop 0
	v_cndmask_b32_e32 v1, v1, v4, vcc
	v_add_u32_e32 v4, 1, v3
	v_mad_u64_u32 v[2:3], s[0:1], v2, v1, v[2:3]
	v_cmp_ne_u32_e32 vcc, v4, v2
	s_and_saveexec_b64 s[0:1], vcc
	s_xor_b64 s[8:9], exec, s[0:1]
	s_cbranch_execz .LBB0_154
	v_mad_u32_u24 v4, v1, v0, v0
	v_mov_b32_e32 v0, 0x3000
	global_load_dword v0, v0, s[92:93] offset:1024 sc1
	s_add_u32 s56, s92, 0x3400
	s_addc_u32 s57, s93, 0
	s_waitcnt vmcnt(0)
	v_cmp_lt_u32_e32 vcc, v0, v4
	s_and_saveexec_b64 s[12:13], vcc
	s_cbranch_execz .LBB0_153
	s_mov_b32 s0, 1
	s_mov_b64 s[60:61], 0
	v_mov_b32_e32 v0, 0
	s_branch .LBB0_144

.LBB0_148:
	global_load_dword v2, v0, s[56:57] sc1
	s_add_i32 s0, s0, 1
	s_mov_b64 s[82:83], -1
	s_waitcnt vmcnt(0)
	v_cmp_ge_u32_e32 vcc, v2, v4
	s_orn2_b64 s[80:81], vcc, exec
	s_branch .LBB0_143

.LBB0_157:
	s_or_b64 exec, exec, s[12:13]
	s_waitcnt vmcnt(0)
	v_readfirstlane_b32 s0, v2
	v_cvt_f32_u32_e32 v2, v0
	v_sub_u32_e32 v3, 0, v0
	v_add_u32_e32 v1, s0, v1
	s_add_u32 s12, s92, 0x3400
	v_rcp_iflag_f32_e32 v2, v2
	s_addc_u32 s13, s93, 0
	s_mov_b64 s[56:57], 0
	v_mul_f32_e32 v2, 0x4f7ffffe, v2
	v_cvt_u32_f32_e32 v2, v2
	v_mul_lo_u32 v3, v3, v2
	v_mul_hi_u32 v3, v2, v3
	v_add_u32_e32 v2, v2, v3
	v_mul_hi_u32 v2, v1, v2
	v_mul_lo_u32 v3, v2, v0
	v_sub_u32_e32 v3, v1, v3
	v_cmp_ge_u32_e32 vcc, v3, v0
	v_add_u32_e32 v4, 1, v2
	s_nop 0
	v_cndmask_b32_e32 v2, v2, v4, vcc
	v_sub_u32_e32 v4, v3, v0
	v_cndmask_b32_e32 v3, v3, v4, vcc
	v_cmp_ge_u32_e32 vcc, v3, v0
	v_add_u32_e32 v3, 1, v2
	s_nop 0
	v_cndmask_b32_e32 v2, v2, v3, vcc
	v_add_u32_e32 v3, 1, v1
	v_mad_u64_u32 v[0:1], s[0:1], v0, v2, v[0:1]
	v_cmp_ne_u32_e32 vcc, v3, v0
	v_mov_b32_e32 v3, v0
	v_mov_b64_e32 v[0:1], s[12:13]
	s_and_saveexec_b64 s[8:9], vcc
	s_cbranch_execz .LBB0_169
	v_mov_b32_e32 v0, 0
	global_load_dword v1, v0, s[12:13] sc1
	s_mov_b64 s[62:63], 0
	s_waitcnt vmcnt(0)
	v_cmp_lt_u32_e32 vcc, v1, v3
	s_and_saveexec_b64 s[60:61], vcc
	s_cbranch_execz .LBB0_168
	s_add_u32 s56, s92, 0x200
	s_addc_u32 s57, s93, 0
	s_mov_b32 s0, 1
	s_branch .LBB0_161

.LBB0_165:
	global_load_dword v1, v0, s[12:13] sc1
	s_add_i32 s0, s0, 1
	s_mov_b64 s[82:83], -1
	s_waitcnt vmcnt(0)
	v_cmp_ge_u32_e32 vcc, v1, v3
	s_orn2_b64 s[96:97], vcc, exec
	s_branch .LBB0_160

.LBB0_171:
	s_or_b64 exec, exec, s[8:9]
	s_mov_b64 s[8:9], exec
	v_mbcnt_lo_u32_b32 v0, s8, 0
	v_mbcnt_hi_u32_b32 v0, s9, v0
	v_cmp_eq_u32_e32 vcc, 0, v0
	s_waitcnt vmcnt(0)
	buffer_inv sc1
	s_and_saveexec_b64 s[12:13], vcc
	s_cbranch_execz .LBB0_173
	s_bcnt1_i32_b64 s0, s[8:9]
	v_mov_b32_e32 v0, 0x2000
	v_mov_b32_e32 v1, s0
.LBB0_173:
	s_or_b64 exec, exec, s[12:13]
	s_waitcnt vmcnt(0)

.LBB0_241:
	s_or_b64 exec, exec, s[12:13]
	s_waitcnt vmcnt(0)
	v_readfirstlane_b32 s0, v3
	v_sub_u32_e32 v4, 0, v2
	s_nop 0
	v_add_u32_e32 v3, s0, v1
	v_cvt_f32_u32_e32 v1, v2
	v_rcp_iflag_f32_e32 v1, v1
	s_nop 0
	v_mul_f32_e32 v1, 0x4f7ffffe, v1
	v_cvt_u32_f32_e32 v1, v1
	v_mul_lo_u32 v4, v4, v1
	v_mul_hi_u32 v4, v1, v4
	v_add_u32_e32 v1, v1, v4
	v_mul_hi_u32 v1, v3, v1
	v_mul_lo_u32 v4, v1, v2
	v_sub_u32_e32 v4, v3, v4
	v_cmp_ge_u32_e32 vcc, v4, v2
	v_add_u32_e32 v5, 1, v1
	s_nop 0
	v_cndmask_b32_e32 v1, v1, v5, vcc
	v_sub_u32_e32 v5, v4, v2
	v_cndmask_b32_e32 v4, v4, v5, vcc
	v_cmp_ge_u32_e32 vcc, v4, v2
	v_add_u32_e32 v4, 1, v1
	s_nop 0
	v_cndmask_b32_e32 v1, v1, v4, vcc
	v_add_u32_e32 v4, 1, v3
	v_mad_u64_u32 v[2:3], s[0:1], v2, v1, v[2:3]
	v_cmp_ne_u32_e32 vcc, v4, v2
	s_and_saveexec_b64 s[0:1], vcc
	s_xor_b64 s[8:9], exec, s[0:1]
	s_cbranch_execz .LBB0_255
	v_mad_u32_u24 v4, v1, v0, v0
	v_mov_b32_e32 v0, 0x3000
	global_load_dword v0, v0, s[92:93] offset:1024 sc1
	s_add_u32 s48, s92, 0x3400
	s_addc_u32 s49, s93, 0
	s_waitcnt vmcnt(0)
	v_cmp_lt_u32_e32 vcc, v0, v4
	s_and_saveexec_b64 s[12:13], vcc
	s_cbranch_execz .LBB0_254
	s_mov_b32 s0, 1
	s_mov_b64 s[56:57], 0
	v_mov_b32_e32 v0, 0
	s_branch .LBB0_245

.LBB0_249:
	global_load_dword v2, v0, s[48:49] sc1
	s_add_i32 s0, s0, 1
	s_mov_b64 s[80:81], -1
	s_waitcnt vmcnt(0)
	v_cmp_ge_u32_e32 vcc, v2, v4
	s_orn2_b64 s[62:63], vcc, exec
	s_branch .LBB0_244

.LBB0_258:
	s_or_b64 exec, exec, s[12:13]
	s_waitcnt vmcnt(0)
	v_readfirstlane_b32 s0, v2
	v_cvt_f32_u32_e32 v2, v0
	v_sub_u32_e32 v3, 0, v0
	v_add_u32_e32 v1, s0, v1
	s_add_u32 s12, s92, 0x3400
	v_rcp_iflag_f32_e32 v2, v2
	s_addc_u32 s13, s93, 0
	s_mov_b64 s[48:49], 0
	v_mul_f32_e32 v2, 0x4f7ffffe, v2
	v_cvt_u32_f32_e32 v2, v2
	v_mul_lo_u32 v3, v3, v2
	v_mul_hi_u32 v3, v2, v3
	v_add_u32_e32 v2, v2, v3
	v_mul_hi_u32 v2, v1, v2
	v_mul_lo_u32 v3, v2, v0
	v_sub_u32_e32 v3, v1, v3
	v_cmp_ge_u32_e32 vcc, v3, v0
	v_add_u32_e32 v4, 1, v2
	s_nop 0
	v_cndmask_b32_e32 v2, v2, v4, vcc
	v_sub_u32_e32 v4, v3, v0
	v_cndmask_b32_e32 v3, v3, v4, vcc
	v_cmp_ge_u32_e32 vcc, v3, v0
	v_add_u32_e32 v3, 1, v2
	s_nop 0
	v_cndmask_b32_e32 v2, v2, v3, vcc
	v_add_u32_e32 v3, 1, v1
	v_mad_u64_u32 v[0:1], s[0:1], v0, v2, v[0:1]
	v_cmp_ne_u32_e32 vcc, v3, v0
	v_mov_b32_e32 v3, v0
	v_mov_b64_e32 v[0:1], s[12:13]
	s_and_saveexec_b64 s[8:9], vcc
	s_cbranch_execz .LBB0_270
	v_mov_b32_e32 v0, 0
	global_load_dword v1, v0, s[12:13] sc1
	s_mov_b64 s[60:61], 0
	s_waitcnt vmcnt(0)
	v_cmp_lt_u32_e32 vcc, v1, v3
	s_and_saveexec_b64 s[56:57], vcc
	s_cbranch_execz .LBB0_269
	s_add_u32 s48, s92, 0x200
	s_addc_u32 s49, s93, 0
	s_mov_b32 s0, 1
	s_branch .LBB0_262

.LBB0_266:
	global_load_dword v1, v0, s[12:13] sc1
	s_add_i32 s0, s0, 1
	s_mov_b64 s[80:81], -1
	s_waitcnt vmcnt(0)
	v_cmp_ge_u32_e32 vcc, v1, v3
	s_orn2_b64 s[94:95], vcc, exec
	s_branch .LBB0_261

.LBB0_272:
	s_or_b64 exec, exec, s[8:9]
	s_mov_b64 s[8:9], exec
	v_mbcnt_lo_u32_b32 v0, s8, 0
	v_mbcnt_hi_u32_b32 v0, s9, v0
	v_cmp_eq_u32_e32 vcc, 0, v0
	s_waitcnt vmcnt(0)
	buffer_inv sc1
	s_and_saveexec_b64 s[12:13], vcc
	s_cbranch_execz .LBB0_274
	s_bcnt1_i32_b64 s0, s[8:9]
	v_mov_b32_e32 v0, 0x2000
	v_mov_b32_e32 v1, s0
.LBB0_274:
	s_or_b64 exec, exec, s[12:13]
	s_waitcnt vmcnt(0)

.LBB0_413:
	s_or_b64 exec, exec, s[10:11]
	s_waitcnt vmcnt(0)
	v_readfirstlane_b32 s0, v3
	v_sub_u32_e32 v4, 0, v2
	s_nop 0
	v_add_u32_e32 v3, s0, v1
	v_cvt_f32_u32_e32 v1, v2
	v_rcp_iflag_f32_e32 v1, v1
	s_nop 0
	v_mul_f32_e32 v1, 0x4f7ffffe, v1
	v_cvt_u32_f32_e32 v1, v1
	v_mul_lo_u32 v4, v4, v1
	v_mul_hi_u32 v4, v1, v4
	v_add_u32_e32 v1, v1, v4
	v_mul_hi_u32 v1, v3, v1
	v_mul_lo_u32 v4, v1, v2
	v_sub_u32_e32 v4, v3, v4
	v_cmp_ge_u32_e32 vcc, v4, v2
	v_add_u32_e32 v5, 1, v1
	s_nop 0
	v_cndmask_b32_e32 v1, v1, v5, vcc
	v_sub_u32_e32 v5, v4, v2
	v_cndmask_b32_e32 v4, v4, v5, vcc
	v_cmp_ge_u32_e32 vcc, v4, v2
	v_add_u32_e32 v4, 1, v1
	s_nop 0
	v_cndmask_b32_e32 v1, v1, v4, vcc
	v_add_u32_e32 v4, 1, v3
	v_mad_u64_u32 v[2:3], s[0:1], v2, v1, v[2:3]
	v_cmp_ne_u32_e32 vcc, v4, v2
	s_and_saveexec_b64 s[0:1], vcc
	s_xor_b64 s[8:9], exec, s[0:1]
	s_cbranch_execz .LBB0_427
	v_mad_u32_u24 v4, v1, v0, v0
	v_mov_b32_e32 v0, 0x3000
	global_load_dword v0, v0, s[92:93] offset:1024 sc1
	s_add_u32 s12, s92, 0x3400
	s_addc_u32 s13, s93, 0
	s_waitcnt vmcnt(0)
	v_cmp_lt_u32_e32 vcc, v0, v4
	s_and_saveexec_b64 s[10:11], vcc
	s_cbranch_execz .LBB0_426
	s_mov_b32 s0, 1
	s_mov_b64 s[48:49], 0
	v_mov_b32_e32 v0, 0
	s_branch .LBB0_417

.LBB0_421:
	global_load_dword v2, v0, s[12:13] sc1
	s_add_i32 s0, s0, 1
	s_mov_b64 s[58:59], -1
	s_waitcnt vmcnt(0)
	v_cmp_ge_u32_e32 vcc, v2, v4
	s_orn2_b64 s[56:57], vcc, exec
	s_branch .LBB0_416

.LBB0_430:
	s_or_b64 exec, exec, s[10:11]
	s_waitcnt vmcnt(0)
	v_readfirstlane_b32 s0, v2
	v_cvt_f32_u32_e32 v2, v0
	v_sub_u32_e32 v3, 0, v0
	v_add_u32_e32 v1, s0, v1
	s_add_u32 s10, s92, 0x3400
	v_rcp_iflag_f32_e32 v2, v2
	s_addc_u32 s11, s93, 0
	s_mov_b64 s[12:13], 0
	v_mul_f32_e32 v2, 0x4f7ffffe, v2
	v_cvt_u32_f32_e32 v2, v2
	v_mul_lo_u32 v3, v3, v2
	v_mul_hi_u32 v3, v2, v3
	v_add_u32_e32 v2, v2, v3
	v_mul_hi_u32 v2, v1, v2
	v_mul_lo_u32 v3, v2, v0
	v_sub_u32_e32 v3, v1, v3
	v_cmp_ge_u32_e32 vcc, v3, v0
	v_add_u32_e32 v4, 1, v2
	s_nop 0
	v_cndmask_b32_e32 v2, v2, v4, vcc
	v_sub_u32_e32 v4, v3, v0
	v_cndmask_b32_e32 v3, v3, v4, vcc
	v_cmp_ge_u32_e32 vcc, v3, v0
	v_add_u32_e32 v3, 1, v2
	s_nop 0
	v_cndmask_b32_e32 v2, v2, v3, vcc
	v_add_u32_e32 v3, 1, v1
	v_mad_u64_u32 v[0:1], s[0:1], v0, v2, v[0:1]
	v_cmp_ne_u32_e32 vcc, v3, v0
	v_mov_b32_e32 v3, v0
	v_mov_b64_e32 v[0:1], s[10:11]
	s_and_saveexec_b64 s[8:9], vcc
	s_cbranch_execz .LBB0_442
	v_mov_b32_e32 v0, 0
	global_load_dword v1, v0, s[10:11] sc1
	s_mov_b64 s[54:55], 0
	s_waitcnt vmcnt(0)
	v_cmp_lt_u32_e32 vcc, v1, v3
	s_and_saveexec_b64 s[48:49], vcc
	s_cbranch_execz .LBB0_441
	s_add_u32 s12, s92, 0x200
	s_addc_u32 s13, s93, 0
	s_mov_b32 s0, 1
	s_branch .LBB0_434

.LBB0_438:
	global_load_dword v1, v0, s[10:11] sc1
	s_add_i32 s0, s0, 1
	s_mov_b64 s[58:59], -1
	s_waitcnt vmcnt(0)
	v_cmp_ge_u32_e32 vcc, v1, v3
	s_orn2_b64 s[62:63], vcc, exec
	s_branch .LBB0_433

.LBB0_444:
	s_or_b64 exec, exec, s[8:9]
	s_mov_b64 s[8:9], exec
	v_mbcnt_lo_u32_b32 v0, s8, 0
	v_mbcnt_hi_u32_b32 v0, s9, v0
	v_cmp_eq_u32_e32 vcc, 0, v0
	s_waitcnt vmcnt(0)
	buffer_inv sc1
	s_and_saveexec_b64 s[10:11], vcc
	s_cbranch_execz .LBB0_446
	s_bcnt1_i32_b64 s0, s[8:9]
	v_mov_b32_e32 v0, 0x2000
	v_mov_b32_e32 v1, s0
.LBB0_446:
	s_or_b64 exec, exec, s[10:11]
	s_waitcnt vmcnt(0)

.LBB0_601:
	s_or_b64 exec, exec, s[22:23]
	v_cvt_f32_u32_e32 v4, v2
	s_waitcnt vmcnt(0)
	v_readfirstlane_b32 s0, v3
	v_rcp_iflag_f32_e32 v4, v4
	s_nop 0
	v_add_u32_e32 v1, s0, v1
	v_add_u32_e32 v5, 1, v1
	v_mul_f32_e32 v3, 0x4f7ffffe, v4
	v_cvt_u32_f32_e32 v3, v3
	v_sub_u32_e32 v4, 0, v2
	v_mul_lo_u32 v4, v4, v3
	v_mul_hi_u32 v4, v3, v4
	v_add_u32_e32 v3, v3, v4
	v_mul_hi_u32 v3, v1, v3
	v_mul_lo_u32 v4, v3, v2
	v_sub_u32_e32 v1, v1, v4
	v_add_u32_e32 v6, 1, v3
	v_cmp_ge_u32_e32 vcc, v1, v2
	v_sub_u32_e32 v4, v1, v2
	s_nop 0
	v_cndmask_b32_e32 v3, v3, v6, vcc
	v_cndmask_b32_e32 v1, v1, v4, vcc
	v_add_u32_e32 v4, 1, v3
	v_cmp_ge_u32_e32 vcc, v1, v2
	s_nop 1
	v_cndmask_b32_e32 v1, v3, v4, vcc
	v_mad_u64_u32 v[2:3], s[0:1], v2, v1, v[2:3]
	v_cmp_ne_u32_e32 vcc, v5, v2
	s_and_saveexec_b64 s[0:1], vcc
	s_xor_b64 s[20:21], exec, s[0:1]
	s_cbranch_execz .LBB0_615
	v_mad_u32_u24 v5, v1, v0, v0
	v_mov_b32_e32 v0, 0x3000
	global_load_dword v0, v0, s[92:93] offset:1024 sc1
	s_add_u32 s48, s92, 0x3400
	s_addc_u32 s49, s93, 0
	s_waitcnt vmcnt(0)
	v_cmp_lt_u32_e32 vcc, v0, v5
	s_and_saveexec_b64 s[22:23], vcc
	s_cbranch_execz .LBB0_614
	s_mov_b32 s0, 1
	s_mov_b64 s[54:55], 0
	v_mov_b32_e32 v0, 0
	s_branch .LBB0_605

.LBB0_609:
	global_load_dword v2, v0, s[48:49] sc1
	s_add_i32 s0, s0, 1
	s_mov_b64 s[60:61], -1
	s_waitcnt vmcnt(0)
	v_cmp_ge_u32_e32 vcc, v2, v5
	s_orn2_b64 s[58:59], vcc, exec
	s_branch .LBB0_604

.LBB0_618:
	s_or_b64 exec, exec, s[22:23]
	v_cvt_f32_u32_e32 v3, v0
	s_waitcnt vmcnt(0)
	v_readfirstlane_b32 s0, v2
	s_add_u32 s22, s92, 0x3400
	s_addc_u32 s23, s93, 0
	v_rcp_iflag_f32_e32 v3, v3
	v_add_u32_e32 v1, s0, v1
	v_add_u32_e32 v4, 1, v1
	s_mov_b64 s[48:49], 0
	v_mul_f32_e32 v2, 0x4f7ffffe, v3
	v_cvt_u32_f32_e32 v2, v2
	v_sub_u32_e32 v3, 0, v0
	v_mul_lo_u32 v3, v3, v2
	v_mul_hi_u32 v3, v2, v3
	v_add_u32_e32 v2, v2, v3
	v_mul_hi_u32 v2, v1, v2
	v_mul_lo_u32 v3, v2, v0
	v_sub_u32_e32 v1, v1, v3
	v_add_u32_e32 v5, 1, v2
	v_cmp_ge_u32_e32 vcc, v1, v0
	v_sub_u32_e32 v3, v1, v0
	s_nop 0
	v_cndmask_b32_e32 v2, v2, v5, vcc
	v_cndmask_b32_e32 v1, v1, v3, vcc
	v_add_u32_e32 v3, 1, v2
	v_cmp_ge_u32_e32 vcc, v1, v0
	s_nop 1
	v_cndmask_b32_e32 v2, v2, v3, vcc
	v_mad_u64_u32 v[0:1], s[0:1], v0, v2, v[0:1]
	v_cmp_ne_u32_e32 vcc, v4, v0
	v_mov_b32_e32 v4, v0
	v_mov_b64_e32 v[0:1], s[22:23]
	s_and_saveexec_b64 s[20:21], vcc
	s_cbranch_execz .LBB0_630
	v_mov_b32_e32 v0, 0
	global_load_dword v1, v0, s[22:23] sc1
	s_mov_b64 s[56:57], 0
	s_waitcnt vmcnt(0)
	v_cmp_lt_u32_e32 vcc, v1, v4
	s_and_saveexec_b64 s[54:55], vcc
	s_cbranch_execz .LBB0_629
	s_add_u32 s48, s92, 0x200
	s_addc_u32 s49, s93, 0
	s_mov_b32 s0, 1
	s_branch .LBB0_622

.LBB0_626:
	global_load_dword v1, v0, s[22:23] sc1
	s_add_i32 s0, s0, 1
	s_mov_b64 s[60:61], -1
	s_waitcnt vmcnt(0)
	v_cmp_ge_u32_e32 vcc, v1, v4
	s_orn2_b64 s[64:65], vcc, exec
	s_branch .LBB0_621

.LBB0_632:
	s_or_b64 exec, exec, s[20:21]
	s_mov_b64 s[20:21], exec
	v_mbcnt_lo_u32_b32 v0, s20, 0
	v_mbcnt_hi_u32_b32 v0, s21, v0
	v_cmp_eq_u32_e32 vcc, 0, v0
	s_waitcnt vmcnt(0)
	buffer_inv sc1
	s_and_saveexec_b64 s[22:23], vcc
	s_cbranch_execz .LBB0_634
	s_bcnt1_i32_b64 s0, s[20:21]
	v_mov_b32_e32 v0, 0x2000
	v_mov_b32_e32 v1, s0
.LBB0_634:
	s_or_b64 exec, exec, s[22:23]
	s_waitcnt vmcnt(0)

.LBB0_688:
	s_or_b64 exec, exec, s[20:21]
	v_cvt_f32_u32_e32 v4, v2
	s_waitcnt vmcnt(0)
	v_readfirstlane_b32 s0, v3
	v_rcp_iflag_f32_e32 v4, v4
	s_nop 0
	v_add_u32_e32 v1, s0, v1
	v_add_u32_e32 v5, 1, v1
	v_mul_f32_e32 v3, 0x4f7ffffe, v4
	v_cvt_u32_f32_e32 v3, v3
	v_sub_u32_e32 v4, 0, v2
	v_mul_lo_u32 v4, v4, v3
	v_mul_hi_u32 v4, v3, v4
	v_add_u32_e32 v3, v3, v4
	v_mul_hi_u32 v3, v1, v3
	v_mul_lo_u32 v4, v3, v2
	v_sub_u32_e32 v1, v1, v4
	v_add_u32_e32 v6, 1, v3
	v_cmp_ge_u32_e32 vcc, v1, v2
	v_sub_u32_e32 v4, v1, v2
	s_nop 0
	v_cndmask_b32_e32 v3, v3, v6, vcc
	v_cndmask_b32_e32 v1, v1, v4, vcc
	v_add_u32_e32 v4, 1, v3
	v_cmp_ge_u32_e32 vcc, v1, v2
	s_nop 1
	v_cndmask_b32_e32 v1, v3, v4, vcc
	v_mad_u64_u32 v[2:3], s[0:1], v2, v1, v[2:3]
	v_cmp_ne_u32_e32 vcc, v5, v2
	s_and_saveexec_b64 s[0:1], vcc
	s_xor_b64 s[16:17], exec, s[0:1]
	s_cbranch_execz .LBB0_702
	v_mad_u32_u24 v5, v1, v0, v0
	v_mov_b32_e32 v0, 0x3000
	global_load_dword v0, v0, s[92:93] offset:1024 sc1
	s_add_u32 s22, s92, 0x3400
	s_addc_u32 s23, s93, 0
	s_waitcnt vmcnt(0)
	v_cmp_lt_u32_e32 vcc, v0, v5
	s_and_saveexec_b64 s[20:21], vcc
	s_cbranch_execz .LBB0_701
	s_mov_b32 s0, 1
	s_mov_b64 s[24:25], 0
	v_mov_b32_e32 v0, 0
	s_branch .LBB0_692

.LBB0_696:
	global_load_dword v2, v0, s[22:23] sc1
	s_add_i32 s0, s0, 1
	s_mov_b64 s[52:53], -1
	s_waitcnt vmcnt(0)
	v_cmp_ge_u32_e32 vcc, v2, v5
	s_orn2_b64 s[48:49], vcc, exec
	s_branch .LBB0_691

.LBB0_705:
	s_or_b64 exec, exec, s[20:21]
	v_cvt_f32_u32_e32 v3, v0
	s_waitcnt vmcnt(0)
	v_readfirstlane_b32 s0, v2
	s_add_u32 s20, s92, 0x3400
	s_addc_u32 s21, s93, 0
	v_rcp_iflag_f32_e32 v3, v3
	v_add_u32_e32 v1, s0, v1
	v_add_u32_e32 v4, 1, v1
	s_mov_b64 s[22:23], 0
	v_mul_f32_e32 v2, 0x4f7ffffe, v3
	v_cvt_u32_f32_e32 v2, v2
	v_sub_u32_e32 v3, 0, v0
	v_mul_lo_u32 v3, v3, v2
	v_mul_hi_u32 v3, v2, v3
	v_add_u32_e32 v2, v2, v3
	v_mul_hi_u32 v2, v1, v2
	v_mul_lo_u32 v3, v2, v0
	v_sub_u32_e32 v1, v1, v3
	v_add_u32_e32 v5, 1, v2
	v_cmp_ge_u32_e32 vcc, v1, v0
	v_sub_u32_e32 v3, v1, v0
	s_nop 0
	v_cndmask_b32_e32 v2, v2, v5, vcc
	v_cndmask_b32_e32 v1, v1, v3, vcc
	v_add_u32_e32 v3, 1, v2
	v_cmp_ge_u32_e32 vcc, v1, v0
	s_nop 1
	v_cndmask_b32_e32 v2, v2, v3, vcc
	v_mad_u64_u32 v[0:1], s[0:1], v0, v2, v[0:1]
	v_cmp_ne_u32_e32 vcc, v4, v0
	v_mov_b32_e32 v4, v0
	v_mov_b64_e32 v[0:1], s[20:21]
	s_and_saveexec_b64 s[16:17], vcc
	s_cbranch_execz .LBB0_717
	v_mov_b32_e32 v0, 0
	global_load_dword v1, v0, s[20:21] sc1
	s_mov_b64 s[26:27], 0
	s_waitcnt vmcnt(0)
	v_cmp_lt_u32_e32 vcc, v1, v4
	s_and_saveexec_b64 s[24:25], vcc
	s_cbranch_execz .LBB0_716
	s_add_u32 s22, s92, 0x200
	s_addc_u32 s23, s93, 0
	s_mov_b32 s0, 1
	s_branch .LBB0_709

.LBB0_713:
	global_load_dword v1, v0, s[20:21] sc1
	s_add_i32 s0, s0, 1
	s_mov_b64 s[52:53], -1
	s_waitcnt vmcnt(0)
	v_cmp_ge_u32_e32 vcc, v1, v4
	s_orn2_b64 s[56:57], vcc, exec
	s_branch .LBB0_708

.LBB0_719:
	s_or_b64 exec, exec, s[16:17]
	s_mov_b64 s[16:17], exec
	v_mbcnt_lo_u32_b32 v0, s16, 0
	v_mbcnt_hi_u32_b32 v0, s17, v0
	v_cmp_eq_u32_e32 vcc, 0, v0
	s_waitcnt vmcnt(0)
	buffer_inv sc1
	s_and_saveexec_b64 s[20:21], vcc
	s_cbranch_execz .LBB0_721
	s_bcnt1_i32_b64 s0, s[16:17]
	v_mov_b32_e32 v0, 0x2000
	v_mov_b32_e32 v1, s0
.LBB0_721:
	s_or_b64 exec, exec, s[20:21]
	s_waitcnt vmcnt(0)

.LBB0_788:
	s_or_b64 exec, exec, s[22:23]
	v_cvt_f32_u32_e32 v4, v2
	s_waitcnt vmcnt(0)
	v_readfirstlane_b32 s0, v3
	v_rcp_iflag_f32_e32 v4, v4
	s_nop 0
	v_add_u32_e32 v1, s0, v1
	v_add_u32_e32 v5, 1, v1
	v_mul_f32_e32 v3, 0x4f7ffffe, v4
	v_cvt_u32_f32_e32 v3, v3
	v_sub_u32_e32 v4, 0, v2
	v_mul_lo_u32 v4, v4, v3
	v_mul_hi_u32 v4, v3, v4
	v_add_u32_e32 v3, v3, v4
	v_mul_hi_u32 v3, v1, v3
	v_mul_lo_u32 v4, v3, v2
	v_sub_u32_e32 v1, v1, v4
	v_add_u32_e32 v6, 1, v3
	v_cmp_ge_u32_e32 vcc, v1, v2
	v_sub_u32_e32 v4, v1, v2
	s_nop 0
	v_cndmask_b32_e32 v3, v3, v6, vcc
	v_cndmask_b32_e32 v1, v1, v4, vcc
	v_add_u32_e32 v4, 1, v3
	v_cmp_ge_u32_e32 vcc, v1, v2
	s_nop 1
	v_cndmask_b32_e32 v1, v3, v4, vcc
	v_mad_u64_u32 v[2:3], s[0:1], v2, v1, v[2:3]
	v_cmp_ne_u32_e32 vcc, v5, v2
	s_and_saveexec_b64 s[0:1], vcc
	s_xor_b64 s[20:21], exec, s[0:1]
	s_cbranch_execz .LBB0_802
	v_mad_u32_u24 v5, v1, v0, v0
	v_mov_b32_e32 v0, 0x3000
	global_load_dword v0, v0, s[92:93] offset:1024 sc1
	s_add_u32 s24, s92, 0x3400
	s_addc_u32 s25, s93, 0
	s_waitcnt vmcnt(0)
	v_cmp_lt_u32_e32 vcc, v0, v5
	s_and_saveexec_b64 s[22:23], vcc
	s_cbranch_execz .LBB0_801
	s_mov_b32 s0, 1
	s_mov_b64 s[26:27], 0
	v_mov_b32_e32 v0, 0
	s_branch .LBB0_792

.LBB0_796:
	global_load_dword v2, v0, s[24:25] sc1
	s_add_i32 s0, s0, 1
	s_mov_b64 s[52:53], -1
	s_waitcnt vmcnt(0)
	v_cmp_ge_u32_e32 vcc, v2, v5
	s_orn2_b64 s[50:51], vcc, exec
	s_branch .LBB0_791

.LBB0_805:
	s_or_b64 exec, exec, s[22:23]
	v_cvt_f32_u32_e32 v3, v0
	s_waitcnt vmcnt(0)
	v_readfirstlane_b32 s0, v2
	s_add_u32 s22, s92, 0x3400
	s_addc_u32 s23, s93, 0
	v_rcp_iflag_f32_e32 v3, v3
	v_add_u32_e32 v1, s0, v1
	v_add_u32_e32 v4, 1, v1
	s_mov_b64 s[24:25], 0
	v_mul_f32_e32 v2, 0x4f7ffffe, v3
	v_cvt_u32_f32_e32 v2, v2
	v_sub_u32_e32 v3, 0, v0
	v_mul_lo_u32 v3, v3, v2
	v_mul_hi_u32 v3, v2, v3
	v_add_u32_e32 v2, v2, v3
	v_mul_hi_u32 v2, v1, v2
	v_mul_lo_u32 v3, v2, v0
	v_sub_u32_e32 v1, v1, v3
	v_add_u32_e32 v5, 1, v2
	v_cmp_ge_u32_e32 vcc, v1, v0
	v_sub_u32_e32 v3, v1, v0
	s_nop 0
	v_cndmask_b32_e32 v2, v2, v5, vcc
	v_cndmask_b32_e32 v1, v1, v3, vcc
	v_add_u32_e32 v3, 1, v2
	v_cmp_ge_u32_e32 vcc, v1, v0
	s_nop 1
	v_cndmask_b32_e32 v2, v2, v3, vcc
	v_mad_u64_u32 v[0:1], s[0:1], v0, v2, v[0:1]
	v_cmp_ne_u32_e32 vcc, v4, v0
	v_mov_b32_e32 v4, v0
	v_mov_b64_e32 v[0:1], s[22:23]
	s_and_saveexec_b64 s[20:21], vcc
	s_cbranch_execz .LBB0_817
	v_mov_b32_e32 v0, 0
	global_load_dword v1, v0, s[22:23] sc1
	s_mov_b64 s[48:49], 0
	s_waitcnt vmcnt(0)
	v_cmp_lt_u32_e32 vcc, v1, v4
	s_and_saveexec_b64 s[26:27], vcc
	s_cbranch_execz .LBB0_816
	s_add_u32 s24, s92, 0x200
	s_addc_u32 s25, s93, 0
	s_mov_b32 s0, 1
	s_branch .LBB0_809

.LBB0_813:
	global_load_dword v1, v0, s[22:23] sc1
	s_add_i32 s0, s0, 1
	s_mov_b64 s[52:53], -1
	s_waitcnt vmcnt(0)
	v_cmp_ge_u32_e32 vcc, v1, v4
	s_orn2_b64 s[56:57], vcc, exec
	s_branch .LBB0_808

.LBB0_819:
	s_or_b64 exec, exec, s[20:21]
	s_mov_b64 s[20:21], exec
	v_mbcnt_lo_u32_b32 v0, s20, 0
	v_mbcnt_hi_u32_b32 v0, s21, v0
	v_cmp_eq_u32_e32 vcc, 0, v0
	s_waitcnt vmcnt(0)
	buffer_inv sc1
	s_and_saveexec_b64 s[22:23], vcc
	s_cbranch_execz .LBB0_821
	s_bcnt1_i32_b64 s0, s[20:21]
	v_mov_b32_e32 v0, 0x2000
	v_mov_b32_e32 v1, s0
.LBB0_821:
	s_or_b64 exec, exec, s[22:23]
	s_waitcnt vmcnt(0)

.LBB0_875:
	s_or_b64 exec, exec, s[20:21]
	s_mov_b64 s[20:21], exec
	v_mbcnt_lo_u32_b32 v0, s20, 0
	v_mbcnt_hi_u32_b32 v0, s21, v0
	v_cmp_eq_u32_e32 vcc, 0, v0
	s_waitcnt vmcnt(0)
	buffer_inv sc1
	s_and_saveexec_b64 s[22:23], vcc
	s_cbranch_execz .LBB0_877
	s_bcnt1_i32_b64 s0, s[20:21]
	v_mov_b32_e32 v0, 0x2000
	v_mov_b32_e32 v1, s0
.LBB0_877:
	s_or_b64 exec, exec, s[22:23]
	s_waitcnt vmcnt(0)

.LBB0_947:
	s_or_b64 exec, exec, s[10:11]
	v_cvt_f32_u32_e32 v4, v2
	s_waitcnt vmcnt(0)
	v_readfirstlane_b32 s0, v3
	v_rcp_iflag_f32_e32 v4, v4
	s_nop 0
	v_add_u32_e32 v1, s0, v1
	v_add_u32_e32 v5, 1, v1
	v_mul_f32_e32 v3, 0x4f7ffffe, v4
	v_cvt_u32_f32_e32 v3, v3
	v_sub_u32_e32 v4, 0, v2
	v_mul_lo_u32 v4, v4, v3
	v_mul_hi_u32 v4, v3, v4
	v_add_u32_e32 v3, v3, v4
	v_mul_hi_u32 v3, v1, v3
	v_mul_lo_u32 v4, v3, v2
	v_sub_u32_e32 v1, v1, v4
	v_add_u32_e32 v6, 1, v3
	v_cmp_ge_u32_e32 vcc, v1, v2
	v_sub_u32_e32 v4, v1, v2
	s_nop 0
	v_cndmask_b32_e32 v3, v3, v6, vcc
	v_cndmask_b32_e32 v1, v1, v4, vcc
	v_add_u32_e32 v4, 1, v3
	v_cmp_ge_u32_e32 vcc, v1, v2
	s_nop 1
	v_cndmask_b32_e32 v1, v3, v4, vcc
	v_mad_u64_u32 v[2:3], s[0:1], v2, v1, v[2:3]
	v_cmp_ne_u32_e32 vcc, v5, v2
	s_and_saveexec_b64 s[0:1], vcc
	s_xor_b64 s[8:9], exec, s[0:1]
	s_cbranch_execz .LBB0_961
	v_mad_u32_u24 v5, v1, v0, v0
	v_mov_b32_e32 v0, 0x3000
	global_load_dword v0, v0, s[92:93] offset:1024 sc1
	s_add_u32 s12, s92, 0x3400
	s_addc_u32 s13, s93, 0
	s_waitcnt vmcnt(0)
	v_cmp_lt_u32_e32 vcc, v0, v5
	s_and_saveexec_b64 s[10:11], vcc
	s_cbranch_execz .LBB0_960
	s_mov_b32 s0, 1
	s_mov_b64 s[16:17], 0
	v_mov_b32_e32 v0, 0
	s_branch .LBB0_951

.LBB0_955:
	global_load_dword v2, v0, s[12:13] sc1
	s_add_i32 s0, s0, 1
	s_mov_b64 s[24:25], -1
	s_waitcnt vmcnt(0)
	v_cmp_ge_u32_e32 vcc, v2, v5
	s_orn2_b64 s[22:23], vcc, exec
	s_branch .LBB0_950

.LBB0_964:
	s_or_b64 exec, exec, s[10:11]
	v_cvt_f32_u32_e32 v3, v0
	s_waitcnt vmcnt(0)
	v_readfirstlane_b32 s0, v2
	s_add_u32 s10, s92, 0x3400
	s_addc_u32 s11, s93, 0
	v_rcp_iflag_f32_e32 v3, v3
	v_add_u32_e32 v1, s0, v1
	v_add_u32_e32 v4, 1, v1
	s_mov_b64 s[12:13], 0
	v_mul_f32_e32 v2, 0x4f7ffffe, v3
	v_cvt_u32_f32_e32 v2, v2
	v_sub_u32_e32 v3, 0, v0
	v_mul_lo_u32 v3, v3, v2
	v_mul_hi_u32 v3, v2, v3
	v_add_u32_e32 v2, v2, v3
	v_mul_hi_u32 v2, v1, v2
	v_mul_lo_u32 v3, v2, v0
	v_sub_u32_e32 v1, v1, v3
	v_add_u32_e32 v5, 1, v2
	v_cmp_ge_u32_e32 vcc, v1, v0
	v_sub_u32_e32 v3, v1, v0
	s_nop 0
	v_cndmask_b32_e32 v2, v2, v5, vcc
	v_cndmask_b32_e32 v1, v1, v3, vcc
	v_add_u32_e32 v3, 1, v2
	v_cmp_ge_u32_e32 vcc, v1, v0
	s_nop 1
	v_cndmask_b32_e32 v2, v2, v3, vcc
	v_mad_u64_u32 v[0:1], s[0:1], v0, v2, v[0:1]
	v_cmp_ne_u32_e32 vcc, v4, v0
	v_mov_b32_e32 v4, v0
	v_mov_b64_e32 v[0:1], s[10:11]
	s_and_saveexec_b64 s[8:9], vcc
	s_cbranch_execz .LBB0_976
	v_mov_b32_e32 v0, 0
	global_load_dword v1, v0, s[10:11] sc1
	s_mov_b64 s[20:21], 0
	s_waitcnt vmcnt(0)
	v_cmp_lt_u32_e32 vcc, v1, v4
	s_and_saveexec_b64 s[16:17], vcc
	s_cbranch_execz .LBB0_975
	s_add_u32 s12, s92, 0x200
	s_addc_u32 s13, s93, 0
	s_mov_b32 s0, 1
	s_branch .LBB0_968

.LBB0_972:
	global_load_dword v1, v0, s[10:11] sc1
	s_add_i32 s0, s0, 1
	s_mov_b64 s[24:25], -1
	s_waitcnt vmcnt(0)
	v_cmp_ge_u32_e32 vcc, v1, v4
	s_orn2_b64 s[48:49], vcc, exec
	s_branch .LBB0_967

.LBB0_978:
	s_or_b64 exec, exec, s[8:9]
	s_mov_b64 s[8:9], exec
	v_mbcnt_lo_u32_b32 v0, s8, 0
	v_mbcnt_hi_u32_b32 v0, s9, v0
	v_cmp_eq_u32_e32 vcc, 0, v0
	s_waitcnt vmcnt(0)
	buffer_inv sc1
	s_and_saveexec_b64 s[10:11], vcc
	s_cbranch_execz .LBB0_980
	s_bcnt1_i32_b64 s0, s[8:9]
	v_mov_b32_e32 v0, 0x2000
	v_mov_b32_e32 v1, s0
.LBB0_980:
	s_or_b64 exec, exec, s[10:11]
	s_waitcnt vmcnt(0)

.LBB0_1004:
	s_or_b64 exec, exec, s[10:11]
	v_cvt_f32_u32_e32 v4, v2
	s_waitcnt vmcnt(0)
	v_readfirstlane_b32 s0, v3
	v_rcp_iflag_f32_e32 v4, v4
	s_nop 0
	v_add_u32_e32 v1, s0, v1
	v_add_u32_e32 v5, 1, v1
	v_mul_f32_e32 v3, 0x4f7ffffe, v4
	v_cvt_u32_f32_e32 v3, v3
	v_sub_u32_e32 v4, 0, v2
	v_mul_lo_u32 v4, v4, v3
	v_mul_hi_u32 v4, v3, v4
	v_add_u32_e32 v3, v3, v4
	v_mul_hi_u32 v3, v1, v3
	v_mul_lo_u32 v4, v3, v2
	v_sub_u32_e32 v1, v1, v4
	v_add_u32_e32 v6, 1, v3
	v_cmp_ge_u32_e32 vcc, v1, v2
	v_sub_u32_e32 v4, v1, v2
	s_nop 0
	v_cndmask_b32_e32 v3, v3, v6, vcc
	v_cndmask_b32_e32 v1, v1, v4, vcc
	v_add_u32_e32 v4, 1, v3
	v_cmp_ge_u32_e32 vcc, v1, v2
	s_nop 1
	v_cndmask_b32_e32 v1, v3, v4, vcc
	v_mad_u64_u32 v[2:3], s[0:1], v2, v1, v[2:3]
	v_cmp_ne_u32_e32 vcc, v5, v2
	s_and_saveexec_b64 s[0:1], vcc
	s_xor_b64 s[8:9], exec, s[0:1]
	s_cbranch_execz .LBB0_1018
	v_mad_u32_u24 v5, v1, v0, v0
	v_mov_b32_e32 v0, 0x3000
	global_load_dword v0, v0, s[92:93] offset:1024 sc1
	s_add_u32 s12, s92, 0x3400
	s_addc_u32 s13, s93, 0
	s_waitcnt vmcnt(0)
	v_cmp_lt_u32_e32 vcc, v0, v5
	s_and_saveexec_b64 s[10:11], vcc
	s_cbranch_execz .LBB0_1017
	s_mov_b32 s0, 1
	s_mov_b64 s[14:15], 0
	v_mov_b32_e32 v0, 0
	s_branch .LBB0_1008

.LBB0_1012:
	global_load_dword v2, v0, s[12:13] sc1
	s_add_i32 s0, s0, 1
	s_mov_b64 s[22:23], -1
	s_waitcnt vmcnt(0)
	v_cmp_ge_u32_e32 vcc, v2, v5
	s_orn2_b64 s[20:21], vcc, exec
	s_branch .LBB0_1007

.LBB0_1021:
	s_or_b64 exec, exec, s[10:11]
	v_cvt_f32_u32_e32 v3, v0
	s_waitcnt vmcnt(0)
	v_readfirstlane_b32 s0, v2
	s_add_u32 s10, s92, 0x3400
	s_addc_u32 s11, s93, 0
	v_rcp_iflag_f32_e32 v3, v3
	v_add_u32_e32 v1, s0, v1
	v_add_u32_e32 v4, 1, v1
	s_mov_b64 s[12:13], 0
	v_mul_f32_e32 v2, 0x4f7ffffe, v3
	v_cvt_u32_f32_e32 v2, v2
	v_sub_u32_e32 v3, 0, v0
	v_mul_lo_u32 v3, v3, v2
	v_mul_hi_u32 v3, v2, v3
	v_add_u32_e32 v2, v2, v3
	v_mul_hi_u32 v2, v1, v2
	v_mul_lo_u32 v3, v2, v0
	v_sub_u32_e32 v1, v1, v3
	v_add_u32_e32 v5, 1, v2
	v_cmp_ge_u32_e32 vcc, v1, v0
	v_sub_u32_e32 v3, v1, v0
	s_nop 0
	v_cndmask_b32_e32 v2, v2, v5, vcc
	v_cndmask_b32_e32 v1, v1, v3, vcc
	v_add_u32_e32 v3, 1, v2
	v_cmp_ge_u32_e32 vcc, v1, v0
	s_nop 1
	v_cndmask_b32_e32 v2, v2, v3, vcc
	v_mad_u64_u32 v[0:1], s[0:1], v0, v2, v[0:1]
	v_cmp_ne_u32_e32 vcc, v4, v0
	v_mov_b32_e32 v4, v0
	v_mov_b64_e32 v[0:1], s[10:11]
	s_and_saveexec_b64 s[8:9], vcc
	s_cbranch_execz .LBB0_1033
	v_mov_b32_e32 v0, 0
	global_load_dword v1, v0, s[10:11] sc1
	s_mov_b64 s[16:17], 0
	s_waitcnt vmcnt(0)
	v_cmp_lt_u32_e32 vcc, v1, v4
	s_and_saveexec_b64 s[14:15], vcc
	s_cbranch_execz .LBB0_1032
	s_add_u32 s12, s92, 0x200
	s_addc_u32 s13, s93, 0
	s_mov_b32 s0, 1
	s_branch .LBB0_1025

.LBB0_1029:
	global_load_dword v1, v0, s[10:11] sc1
	s_add_i32 s0, s0, 1
	s_mov_b64 s[22:23], -1
	s_waitcnt vmcnt(0)
	v_cmp_ge_u32_e32 vcc, v1, v4
	s_orn2_b64 s[26:27], vcc, exec
	s_branch .LBB0_1024

.LBB0_1035:
	s_or_b64 exec, exec, s[8:9]
	s_mov_b64 s[8:9], exec
	v_mbcnt_lo_u32_b32 v0, s8, 0
	v_mbcnt_hi_u32_b32 v0, s9, v0
	v_cmp_eq_u32_e32 vcc, 0, v0
	s_waitcnt vmcnt(0)
	buffer_inv sc1
	s_and_saveexec_b64 s[10:11], vcc
	s_cbranch_execz .LBB0_1037
	s_bcnt1_i32_b64 s0, s[8:9]
	v_mov_b32_e32 v0, 0x2000
	v_mov_b32_e32 v1, s0
.LBB0_1037:
	s_or_b64 exec, exec, s[10:11]
	s_waitcnt vmcnt(0)
